# 1 Mi pieces of the layer-0 cache conversion also deferred (into the P1 tail slot of layer 0)
# baseline (speedup 1.0000x reference)
; DEVI u32x4 pack8(const f32x4 a, const f32x4 b) { u32x4 w; w.x = cvtpk(a[0], a[1]); w.y = cvtpk(a[2], a[3]); w.z = cvtpk(b[0], b[1]); w.w = cvtpk(b[2], b[3]); return w; }
; DEVI const float* IN(int i) { return *(const float* const __attribute__((address_space(4)))*)(kargs() + 8 * i); }
; DEVI void prologue(int wv, LAS unsigned char* lds) {
;     ...
;         const float* cache_ckv = IN(2); bf16_t* ckvb = (bf16_t*)(ws + O_CKVB);
;         for (size_t i = gt; i < (size_t)2 * MC * 256 / 8; i += 8 * NGT) {
;             f32x4 a[8], b[8];
; #pragma unroll
;             for (int k = 0; k < 8; ++k) { const size_t ii = i + k * NGT; if (ii < (size_t)2 * MC * 256 / 8) { a[k] = *(const f32x4*)(cache_ckv + ii * 8); b[k] = *(const f32x4*)(cache_ckv + ii * 8 + 4); } }
; #pragma unroll
;             for (int k = 0; k < 8; ++k) { const size_t ii = i + k * NGT; if (ii < (size_t)2 * MC * 256 / 8) *(u32x4*)(ckvb + ii * 8) = pack8(a[k], b[k]); }
;         }
.LBB0_359:
	s_mov_b64 s[24:25], 0x800000
	s_cmp_lg_u32 s52, 0x35bf
	s_cselect_b32 s24, 0x300000, s24
	s_mov_b64 s[2:3], s[0:1]
	v_cmp_gt_u64_e32 vcc, s[24:25], v[68:69]
	s_and_saveexec_b64 s[26:27], vcc
	s_cbranch_execz .LBB0_390
	s_load_dwordx2 s[28:29], s[2:3], 0x10
	s_lshl_b64 s[2:3], s[18:19], 13
	v_lshl_add_u64 v[0:1], v[64:65], 4, s[2:3]
	s_mov_b64 s[2:3], 0x3bb0800
	v_lshl_add_u64 v[66:67], v[0:1], 0, s[2:3]
	s_lshl_b64 s[2:3], s[18:19], 14
	v_lshlrev_b64 v[0:1], 5, v[64:65]
	s_lshl_b64 s[30:31], s[16:17], 16
	v_lshl_add_u64 v[70:71], s[2:3], 0, v[0:1]
	s_lshl_b64 s[34:35], s[16:17], 17
	s_lshl_b64 s[2:3], s[16:17], 10
	s_add_u32 s2, s2, s6
	s_addc_u32 s3, s3, s7
	v_lshl_add_u64 v[0:1], s[2:3], 0, v[64:65]
	s_add_u32 s2, s6, s22
	s_addc_u32 s3, s7, s23
	v_lshl_add_u64 v[76:77], s[2:3], 0, v[64:65]
	s_lshl_b64 s[36:37], s[16:17], 12
	s_mul_i32 s2, s16, 0x600
	s_mul_hi_i32 s3, s16, 0x600
	s_add_u32 s2, s2, s6
	v_mov_b64_e32 v[2:3], 0x3bb0800
	s_addc_u32 s3, s3, s7
	v_lshlrev_b64 v[72:73], 5, v[0:1]
	v_lshl_add_u64 v[74:75], v[0:1], 4, v[2:3]
	v_lshl_add_u64 v[0:1], s[2:3], 0, v[64:65]
	s_lshl_b64 s[2:3], s[16:17], 11
	s_add_u32 s2, s2, s6
	s_addc_u32 s3, s3, s7
	v_lshlrev_b64 v[78:79], 5, v[0:1]
	v_lshl_add_u64 v[80:81], v[0:1], 4, v[2:3]
	v_lshl_add_u64 v[0:1], s[2:3], 0, v[64:65]
	s_mul_i32 s2, s16, 0xa00
	s_mul_hi_i32 s3, s16, 0xa00
	s_add_u32 s2, s2, s6
	s_addc_u32 s3, s3, s7
	v_lshlrev_b64 v[84:85], 5, v[0:1]
	v_lshl_add_u64 v[86:87], v[0:1], 4, v[2:3]
	v_lshl_add_u64 v[0:1], s[2:3], 0, v[64:65]
	s_mul_i32 s2, s16, 0xe00
	s_mul_hi_i32 s3, s16, 0xe00
	s_add_u32 s2, s2, s6
	s_addc_u32 s3, s3, s7
	v_lshlrev_b64 v[90:91], 5, v[0:1]
	v_lshl_add_u64 v[92:93], v[0:1], 4, v[2:3]
	v_lshl_add_u64 v[0:1], s[2:3], 0, v[64:65]
	s_mul_i32 s2, s16, 0xc00
	s_mul_hi_i32 s3, s16, 0xc00
	s_add_u32 s2, s2, s6
	s_addc_u32 s3, s3, s7
	v_lshl_add_u64 v[4:5], s[2:3], 0, v[64:65]
	v_lshlrev_b64 v[96:97], 5, v[4:5]
	v_lshlrev_b64 v[100:101], 5, v[0:1]
	v_or_b32_e32 v72, 16, v72
	v_or_b32_e32 v78, 16, v78
	v_lshlrev_b64 v[82:83], 5, v[76:77]
	v_or_b32_e32 v84, 16, v84
	v_lshl_add_u64 v[88:89], v[76:77], 4, v[2:3]
	v_or_b32_e32 v90, 16, v90
	v_lshl_add_u64 v[94:95], v[0:1], 4, v[2:3]
	v_or_b32_e32 v96, 16, v96
	v_lshl_add_u64 v[98:99], v[4:5], 4, v[2:3]
	v_or_b32_e32 v100, 16, v100
	v_bfe_u32 v0, v70, 5, 10
	v_and_b32_e32 v70, 0xffff801f, v70
	v_and_b32_e32 v2, 31, v0
	v_lshl_or_b32 v70, v2, 10, v70
	v_lshrrev_b32_e32 v2, 8, v0
	v_lshl_or_b32 v70, v2, 8, v70
	v_bfe_u32 v2, v0, 5, 1
	v_lshl_or_b32 v70, v2, 7, v70
	v_bfe_u32 v2, v0, 6, 2
	v_lshl_or_b32 v70, v2, 5, v70
	v_bfe_u32 v0, v82, 5, 10
	v_and_b32_e32 v82, 0xffff801f, v82
	v_and_b32_e32 v2, 31, v0
	v_lshl_or_b32 v82, v2, 10, v82
	v_lshrrev_b32_e32 v2, 8, v0
	v_lshl_or_b32 v82, v2, 8, v82
	v_bfe_u32 v2, v0, 5, 1
	v_lshl_or_b32 v82, v2, 7, v82
	v_bfe_u32 v2, v0, 6, 2
	v_lshl_or_b32 v82, v2, 5, v82
	v_bfe_u32 v0, v72, 5, 10
	v_and_b32_e32 v72, 0xffff801f, v72
	v_and_b32_e32 v2, 31, v0
	v_lshl_or_b32 v72, v2, 10, v72
	v_lshrrev_b32_e32 v2, 8, v0
	v_lshl_or_b32 v72, v2, 8, v72
	v_bfe_u32 v2, v0, 5, 1
	v_lshl_or_b32 v72, v2, 7, v72
	v_bfe_u32 v2, v0, 6, 2
	v_lshl_or_b32 v72, v2, 5, v72
	v_bfe_u32 v0, v78, 5, 10
	v_and_b32_e32 v78, 0xffff801f, v78
	v_and_b32_e32 v2, 31, v0
	v_lshl_or_b32 v78, v2, 10, v78
	v_lshrrev_b32_e32 v2, 8, v0
	v_lshl_or_b32 v78, v2, 8, v78
	v_bfe_u32 v2, v0, 5, 1
	v_lshl_or_b32 v78, v2, 7, v78
	v_bfe_u32 v2, v0, 6, 2
	v_lshl_or_b32 v78, v2, 5, v78
	v_bfe_u32 v0, v84, 5, 10
	v_and_b32_e32 v84, 0xffff801f, v84
	v_and_b32_e32 v2, 31, v0
	v_lshl_or_b32 v84, v2, 10, v84
	v_lshrrev_b32_e32 v2, 8, v0
	v_lshl_or_b32 v84, v2, 8, v84
	v_bfe_u32 v2, v0, 5, 1
	v_lshl_or_b32 v84, v2, 7, v84
	v_bfe_u32 v2, v0, 6, 2
	v_lshl_or_b32 v84, v2, 5, v84
	v_bfe_u32 v0, v90, 5, 10
	v_and_b32_e32 v90, 0xffff801f, v90
	v_and_b32_e32 v2, 31, v0
	v_lshl_or_b32 v90, v2, 10, v90
	v_lshrrev_b32_e32 v2, 8, v0
	v_lshl_or_b32 v90, v2, 8, v90
	v_bfe_u32 v2, v0, 5, 1
	v_lshl_or_b32 v90, v2, 7, v90
	v_bfe_u32 v2, v0, 6, 2
	v_lshl_or_b32 v90, v2, 5, v90
	v_bfe_u32 v0, v96, 5, 10
	v_and_b32_e32 v96, 0xffff801f, v96
	v_and_b32_e32 v2, 31, v0
	v_lshl_or_b32 v96, v2, 10, v96
	v_lshrrev_b32_e32 v2, 8, v0
	v_lshl_or_b32 v96, v2, 8, v96
	v_bfe_u32 v2, v0, 5, 1
	v_lshl_or_b32 v96, v2, 7, v96
	v_bfe_u32 v2, v0, 6, 2
	v_lshl_or_b32 v96, v2, 5, v96
	v_bfe_u32 v0, v100, 5, 10
	v_and_b32_e32 v100, 0xffff801f, v100
	v_and_b32_e32 v2, 31, v0
	v_lshl_or_b32 v100, v2, 10, v100
	v_lshrrev_b32_e32 v2, 8, v0
	v_lshl_or_b32 v100, v2, 8, v100
	v_bfe_u32 v2, v0, 5, 1
	v_lshl_or_b32 v100, v2, 7, v100
	v_bfe_u32 v2, v0, 6, 2
	v_lshl_or_b32 v100, v2, 5, v100
	s_mov_b64 s[38:39], 0
	s_mov_b64 s[40:41], 0x7fffff
	s_cmp_lg_u32 s52, 0x35bf
	s_cselect_b32 s40, 0x2fffff, s40
	s_waitcnt lgkmcnt(0)
	s_mov_b64 s[42:43], s[20:21]
	s_branch .LBB0_362

; DEVI u32x4 pack8(const f32x4 a, const f32x4 b) { u32x4 w; w.x = cvtpk(a[0], a[1]); w.y = cvtpk(a[2], a[3]); w.z = cvtpk(b[0], b[1]); w.w = cvtpk(b[2], b[3]); return w; }
; DEVI const float* IN(int i) { return *(const float* const __attribute__((address_space(4)))*)(kargs() + 8 * i); }
; DEVI void prologue(int wv, LAS unsigned char* lds) {
;     ...
;         const float* cache_ckv = IN(2); bf16_t* ckvb = (bf16_t*)(ws + O_CKVB);
;         for (size_t i = gt; i < (size_t)2 * MC * 256 / 8; i += 8 * NGT) {
;             f32x4 a[8], b[8];
; #pragma unroll
;             for (int k = 0; k < 8; ++k) { const size_t ii = i + k * NGT; if (ii < (size_t)2 * MC * 256 / 8) { a[k] = *(const f32x4*)(cache_ckv + ii * 8); b[k] = *(const f32x4*)(cache_ckv + ii * 8 + 4); } }
; #pragma unroll
;             for (int k = 0; k < 8; ++k) { const size_t ii = i + k * NGT; if (ii < (size_t)2 * MC * 256 / 8) *(u32x4*)(ckvb + ii * 8) = pack8(a[k], b[k]); }
;         }
.Lsj_ret1:
	v_readlane_b32 vcc_lo, v255, 0
	s_cmp_eq_u32 vcc_lo, 0
	s_cbranch_scc1 .Lsjd_no1_0
	v_readlane_b32 s2, v201, 0
	v_readlane_b32 s3, v201, 1
	v_readlane_b32 s4, v201, 33
	v_readlane_b32 s5, v255, 5
	s_nop 7
	s_load_dwordx2 s[6:7], s[2:3], 0x10
	s_load_dwordx2 s[8:9], s[2:3], 0xb0
	s_sub_i32 s5, s5, 154
	s_and_b32 s5, s5, 0xff
	s_lshl_b32 s5, s5, 9
	v_mbcnt_lo_u32_b32 v0, -1, 0
	v_mbcnt_hi_u32_b32 v0, -1, v0
	v_lshl_or_b32 v0, s4, 6, v0
	v_add_u32_e32 v0, s5, v0
	v_add_u32_e32 v0, 0x300000, v0
	s_mov_b32 s10, 0x400000
	s_waitcnt lgkmcnt(0)
	s_add_u32 s8, s8, 0x3bb0800
	s_addc_u32 s9, s9, 0
.Lsjd_loop1_0:
	v_mov_b32_e32 v1, v0
	v_cmp_gt_u32_e64 s[12:13], s10, v1
	v_add_u32_e32 v2, 0xcc00, v0
	v_cmp_gt_u32_e64 s[14:15], s10, v2
	v_add_u32_e32 v3, 0x19800, v0
	v_cmp_gt_u32_e64 s[16:17], s10, v3
	v_add_u32_e32 v4, 0x26400, v0
	v_cmp_gt_u32_e64 s[18:19], s10, v4
	v_add_u32_e32 v5, 0x33000, v0
	v_cmp_gt_u32_e64 s[20:21], s10, v5
	v_add_u32_e32 v6, 0x3fc00, v0
	v_cmp_gt_u32_e64 s[22:23], s10, v6
	v_add_u32_e32 v7, 0x4c800, v0
	v_cmp_gt_u32_e64 s[24:25], s10, v7
	v_add_u32_e32 v8, 0x59400, v0
	v_cmp_gt_u32_e64 s[26:27], s10, v8
	s_mov_b64 exec, s[12:13]
	v_and_b32_e32 v20, 0x3ff, v1
	v_and_b32_e32 v21, 0xfffffc00, v1
	v_lshlrev_b32_e32 v21, 5, v21
	v_and_b32_e32 v22, 31, v20
	v_lshl_or_b32 v21, v22, 10, v21
	v_lshrrev_b32_e32 v22, 8, v20
	v_lshl_or_b32 v21, v22, 8, v21
	v_bfe_u32 v22, v20, 5, 1
	v_lshl_or_b32 v21, v22, 7, v21
	v_bfe_u32 v22, v20, 6, 2
	v_lshl_or_b32 v9, v22, 5, v21
	global_load_dwordx4 v[24:27], v9, s[6:7]
	global_load_dwordx4 v[28:31], v9, s[6:7] offset:16
	s_mov_b64 exec, s[14:15]
	v_and_b32_e32 v20, 0x3ff, v2
	v_and_b32_e32 v21, 0xfffffc00, v2
	v_lshlrev_b32_e32 v21, 5, v21
	v_and_b32_e32 v22, 31, v20
	v_lshl_or_b32 v21, v22, 10, v21
	v_lshrrev_b32_e32 v22, 8, v20
	v_lshl_or_b32 v21, v22, 8, v21
	v_bfe_u32 v22, v20, 5, 1
	v_lshl_or_b32 v21, v22, 7, v21
	v_bfe_u32 v22, v20, 6, 2
	v_lshl_or_b32 v10, v22, 5, v21
	global_load_dwordx4 v[32:35], v10, s[6:7]
	global_load_dwordx4 v[36:39], v10, s[6:7] offset:16
	s_mov_b64 exec, s[16:17]
	v_and_b32_e32 v20, 0x3ff, v3
	v_and_b32_e32 v21, 0xfffffc00, v3
	v_lshlrev_b32_e32 v21, 5, v21
	v_and_b32_e32 v22, 31, v20
	v_lshl_or_b32 v21, v22, 10, v21
	v_lshrrev_b32_e32 v22, 8, v20
	v_lshl_or_b32 v21, v22, 8, v21
	v_bfe_u32 v22, v20, 5, 1
	v_lshl_or_b32 v21, v22, 7, v21
	v_bfe_u32 v22, v20, 6, 2
	v_lshl_or_b32 v11, v22, 5, v21
	global_load_dwordx4 v[40:43], v11, s[6:7]
	global_load_dwordx4 v[44:47], v11, s[6:7] offset:16
	s_mov_b64 exec, s[18:19]
	v_and_b32_e32 v20, 0x3ff, v4
	v_and_b32_e32 v21, 0xfffffc00, v4
	v_lshlrev_b32_e32 v21, 5, v21
	v_and_b32_e32 v22, 31, v20
	v_lshl_or_b32 v21, v22, 10, v21
	v_lshrrev_b32_e32 v22, 8, v20
	v_lshl_or_b32 v21, v22, 8, v21
	v_bfe_u32 v22, v20, 5, 1
	v_lshl_or_b32 v21, v22, 7, v21
	v_bfe_u32 v22, v20, 6, 2
	v_lshl_or_b32 v12, v22, 5, v21
	global_load_dwordx4 v[48:51], v12, s[6:7]
	global_load_dwordx4 v[52:55], v12, s[6:7] offset:16
	s_mov_b64 exec, s[20:21]
	v_and_b32_e32 v20, 0x3ff, v5
	v_and_b32_e32 v21, 0xfffffc00, v5
	v_lshlrev_b32_e32 v21, 5, v21
	v_and_b32_e32 v22, 31, v20
	v_lshl_or_b32 v21, v22, 10, v21
	v_lshrrev_b32_e32 v22, 8, v20
	v_lshl_or_b32 v21, v22, 8, v21
	v_bfe_u32 v22, v20, 5, 1
	v_lshl_or_b32 v21, v22, 7, v21
	v_bfe_u32 v22, v20, 6, 2
	v_lshl_or_b32 v13, v22, 5, v21
	global_load_dwordx4 v[56:59], v13, s[6:7]
	global_load_dwordx4 v[60:63], v13, s[6:7] offset:16
	s_mov_b64 exec, s[22:23]
	v_and_b32_e32 v20, 0x3ff, v6
	v_and_b32_e32 v21, 0xfffffc00, v6
	v_lshlrev_b32_e32 v21, 5, v21
	v_and_b32_e32 v22, 31, v20
	v_lshl_or_b32 v21, v22, 10, v21
	v_lshrrev_b32_e32 v22, 8, v20
	v_lshl_or_b32 v21, v22, 8, v21
	v_bfe_u32 v22, v20, 5, 1
	v_lshl_or_b32 v21, v22, 7, v21
	v_bfe_u32 v22, v20, 6, 2
	v_lshl_or_b32 v14, v22, 5, v21
	global_load_dwordx4 v[64:67], v14, s[6:7]
	global_load_dwordx4 v[68:71], v14, s[6:7] offset:16
	s_mov_b64 exec, s[24:25]
	v_and_b32_e32 v20, 0x3ff, v7
	v_and_b32_e32 v21, 0xfffffc00, v7
	v_lshlrev_b32_e32 v21, 5, v21
	v_and_b32_e32 v22, 31, v20
	v_lshl_or_b32 v21, v22, 10, v21
	v_lshrrev_b32_e32 v22, 8, v20
	v_lshl_or_b32 v21, v22, 8, v21
	v_bfe_u32 v22, v20, 5, 1
	v_lshl_or_b32 v21, v22, 7, v21
	v_bfe_u32 v22, v20, 6, 2
	v_lshl_or_b32 v15, v22, 5, v21
	global_load_dwordx4 v[72:75], v15, s[6:7]
	global_load_dwordx4 v[76:79], v15, s[6:7] offset:16
	s_mov_b64 exec, s[26:27]
	v_and_b32_e32 v20, 0x3ff, v8
	v_and_b32_e32 v21, 0xfffffc00, v8
	v_lshlrev_b32_e32 v21, 5, v21
	v_and_b32_e32 v22, 31, v20
	v_lshl_or_b32 v21, v22, 10, v21
	v_lshrrev_b32_e32 v22, 8, v20
	v_lshl_or_b32 v21, v22, 8, v21
	v_bfe_u32 v22, v20, 5, 1
	v_lshl_or_b32 v21, v22, 7, v21
	v_bfe_u32 v22, v20, 6, 2
	v_lshl_or_b32 v16, v22, 5, v21
	global_load_dwordx4 v[80:83], v16, s[6:7]
	global_load_dwordx4 v[84:87], v16, s[6:7] offset:16
	s_mov_b64 exec, s[12:13]
	s_waitcnt vmcnt(14)
	v_cvt_pk_bf16_f32 v100, v24, v25
	v_cvt_pk_bf16_f32 v101, v26, v27
	v_cvt_pk_bf16_f32 v102, v28, v29
	v_cvt_pk_bf16_f32 v103, v30, v31
	v_lshlrev_b32_e32 v104, 4, v1
	global_store_dwordx4 v104, v[100:103], s[8:9]
	s_mov_b64 exec, s[14:15]
	s_waitcnt vmcnt(12)
	v_cvt_pk_bf16_f32 v106, v32, v33
	v_cvt_pk_bf16_f32 v107, v34, v35
	v_cvt_pk_bf16_f32 v108, v36, v37
	v_cvt_pk_bf16_f32 v109, v38, v39
	v_lshlrev_b32_e32 v110, 4, v2
	global_store_dwordx4 v110, v[106:109], s[8:9]
	s_mov_b64 exec, s[16:17]
	s_waitcnt vmcnt(10)
	v_cvt_pk_bf16_f32 v100, v40, v41
	v_cvt_pk_bf16_f32 v101, v42, v43
	v_cvt_pk_bf16_f32 v102, v44, v45
	v_cvt_pk_bf16_f32 v103, v46, v47
	v_lshlrev_b32_e32 v104, 4, v3
	global_store_dwordx4 v104, v[100:103], s[8:9]
	s_mov_b64 exec, s[18:19]
	s_waitcnt vmcnt(8)
	v_cvt_pk_bf16_f32 v106, v48, v49
	v_cvt_pk_bf16_f32 v107, v50, v51
	v_cvt_pk_bf16_f32 v108, v52, v53
	v_cvt_pk_bf16_f32 v109, v54, v55
	v_lshlrev_b32_e32 v110, 4, v4
	global_store_dwordx4 v110, v[106:109], s[8:9]
	s_mov_b64 exec, s[20:21]
	s_waitcnt vmcnt(6)
	v_cvt_pk_bf16_f32 v100, v56, v57
	v_cvt_pk_bf16_f32 v101, v58, v59
	v_cvt_pk_bf16_f32 v102, v60, v61
	v_cvt_pk_bf16_f32 v103, v62, v63
	v_lshlrev_b32_e32 v104, 4, v5
	global_store_dwordx4 v104, v[100:103], s[8:9]
	s_mov_b64 exec, s[22:23]
	s_waitcnt vmcnt(4)
	v_cvt_pk_bf16_f32 v106, v64, v65
	v_cvt_pk_bf16_f32 v107, v66, v67
	v_cvt_pk_bf16_f32 v108, v68, v69
	v_cvt_pk_bf16_f32 v109, v70, v71
	v_lshlrev_b32_e32 v110, 4, v6
	global_store_dwordx4 v110, v[106:109], s[8:9]
	s_mov_b64 exec, s[24:25]
	s_waitcnt vmcnt(2)
	v_cvt_pk_bf16_f32 v100, v72, v73
	v_cvt_pk_bf16_f32 v101, v74, v75
	v_cvt_pk_bf16_f32 v102, v76, v77
	v_cvt_pk_bf16_f32 v103, v78, v79
	v_lshlrev_b32_e32 v104, 4, v7
	global_store_dwordx4 v104, v[100:103], s[8:9]
	s_mov_b64 exec, s[26:27]
	s_waitcnt vmcnt(0)
	v_cvt_pk_bf16_f32 v106, v80, v81
	v_cvt_pk_bf16_f32 v107, v82, v83
	v_cvt_pk_bf16_f32 v108, v84, v85
	v_cvt_pk_bf16_f32 v109, v86, v87
	v_lshlrev_b32_e32 v110, 4, v8
	global_store_dwordx4 v110, v[106:109], s[8:9]
	s_mov_b64 exec, -1
	v_add_u32_e32 v0, 0x66000, v0
	v_cmp_gt_u32_e32 vcc, s10, v0
	s_and_b64 vcc, exec, vcc
	s_cbranch_scc1 .Lsjd_loop1_0
; DEVI const float* IN(int i) { return *(const float* const __attribute__((address_space(4)))*)(kargs() + 8 * i); }
; DEVI void prologue(int wv, LAS unsigned char* lds) {
;     ...
;         const float* cache_ckv = IN(2); bf16_t* ckvb = (bf16_t*)(ws + O_CKVB);
;         for (size_t i = gt; i < (size_t)2 * MC * 256 / 8; i += 8 * NGT) {
.Lsjd_no1_0:
	v_readlane_b32 vcc_lo, v255, 0
	s_cmp_lg_u32 vcc_lo, 0
	s_cbranch_scc1 .Lsjd_no1_1
	v_readlane_b32 s2, v201, 0
	v_readlane_b32 s3, v201, 1
	v_readlane_b32 s4, v201, 33
	v_readlane_b32 s5, v255, 5
	s_nop 7
	s_load_dwordx2 s[6:7], s[2:3], 0x10
	s_load_dwordx2 s[8:9], s[2:3], 0xb0
	s_sub_i32 s5, s5, 154
	s_and_b32 s5, s5, 0xff
	s_lshl_b32 s5, s5, 9
	v_mbcnt_lo_u32_b32 v0, -1, 0
	v_mbcnt_hi_u32_b32 v0, -1, v0
	v_lshl_or_b32 v0, s4, 6, v0
	v_add_u32_e32 v0, s5, v0
	v_add_u32_e32 v0, 0x780000, v0
	s_mov_b32 s10, 0x800000
	s_waitcnt lgkmcnt(0)
	s_add_u32 s8, s8, 0x3bb0800
	s_addc_u32 s9, s9, 0
